# EpiConv v2: drop the scaled-rsqrt denormal guard (mean square + eps >= 1e-6 cannot be denormal)
# speedup vs baseline: 1.0319x; 1.0103x over previous
;     __device__ __forceinline__ void operator()(const f32x4 (&acc)[2][2][4][2], const Unit& u, int wr, int wc, int fr, int fq) const {
;         int seqbase, t0, slen; halo_decode(u.pm, seqbase, t0, slen);
;         const f32x4* ct = (const f32x4*)(CT + (size_t)(128 * u.pn) * 8) + (32 * wc + 8 * fq) * 2;
;         const bool f0 = (fr == 0), f15 = (fr == 15);
; #pragma unroll
;         for (int ai = 0; ai < 2; ++ai) {
;             const int tbase = t0 + 62 * (2 * ai + wr) - 1;
;             float rs[4];
; #pragma unroll
;             for (int m = 0; m < 4; ++m) { const int t = tbase + 16 * m + fr; const bool vin = (t >= 0) && (t < slen); const int grow = seqbase + (vin ? t : 0);
;                 const f32x4 p = *(const f32x4*)(PS + (size_t)grow * 16 + 4 * fq); float s = (p[0] + p[1]) + (p[2] + p[3]); s = bfly_add<16>(s); s = bfly_add<32>(s); rs[m] = vin ? rsqrtf(s * (1.f / DM) + EPS) : 0.f; }
;             unsigned outw[4][2][2];
; #pragma unroll
;             for (int n = 0; n < 2; ++n)
; #pragma unroll
;                 for (int jp = 0; jp < 2; ++jp) {
;                     const int cidx = (4 * n + 2 * jp) * 2;
;                     const f32x4 c0a = ct[cidx], c0b = ct[cidx + 1], c1a = ct[cidx + 2], c1b = ct[cidx + 3];
;                     const f32x2 wv0 = {c0a[0], c1a[0]}, wv1 = {c0a[1], c1a[1]}, wv2 = {c0a[2], c1a[2]}, bv = {c0a[3], c1a[3]};
;                     const f32x2 wg0 = {c0b[0], c1b[0]}, wg1 = {c0b[1], c1b[1]}, wg2 = {c0b[2], c1b[2]}, bg = {c0b[3], c1b[3]};
;                     f32x2 uv[4], ug[4], cv[4];
; #pragma unroll
;                     for (int m = 0; m < 4; ++m) { uv[m] = (f32x2){acc[ai][0][m][n][2 * jp], acc[ai][0][m][n][2 * jp + 1]}; ug[m] = (f32x2){acc[ai][1][m][n][2 * jp], acc[ai][1][m][n][2 * jp + 1]}; }
;                     asm volatile("" : "+v"(uv[0]), "+v"(uv[1]), "+v"(uv[2]), "+v"(uv[3]), "+v"(ug[0]), "+v"(ug[1]), "+v"(ug[2]), "+v"(ug[3]));
;                     {
;                         f32x2 rv[4], lv[4];
; #pragma unroll
;                         for (int m = 0; m < 4; ++m) { uv[m] = uv[m] * rs[m]; rv[m] = (f32x2){dpp_ror1(uv[m][0]), dpp_ror1(uv[m][1])}; lv[m] = (f32x2){dpp_ror15(uv[m][0]), dpp_ror15(uv[m][1])}; }
; #pragma unroll
;                         for (int m = 0; m < 4; ++m) { const f32x2 pv_ = (m > 0 && f0) ? rv[m > 0 ? m - 1 : 0] : rv[m], nv_ = (m < 3 && f15) ? lv[m < 3 ? m + 1 : 3] : lv[m];
EC2_join:
	s_mul_i32 s86, s86, 0xf8
	s_bfe_u32 s89, s81, 0x10008
	s_mul_i32 s89, s89, 62
	s_add_i32 s89, s89, s86
	s_add_i32 s89, s89, -1
	v_readlane_b32 s64, v254, 0
	v_readlane_b32 s65, v254, 1
	v_readlane_b32 s66, v255, 4
	s_nop 2
	s_load_dwordx2 s[98:99], s[64:65], 0xe0
	s_mul_i32 s66, s66, 0x16000
	s_bfe_u32 s32, s81, 0x20006
	s_movk_i32 s54, 0x1600
	v_mbcnt_lo_u32_b32 v176, -1, 0
	v_mbcnt_hi_u32_b32 v176, -1, v176
	v_and_b32_e32 v170, 15, v176
	v_lshlrev_b32_e32 v170, 2, v170
	v_bfe_u32 v171, v176, 4, 2
	v_lshlrev_b32_e32 v172, 8, v171
	v_lshlrev_b32_e32 v171, 4, v171
	v_mov_b32_e32 v252, s78
	s_waitcnt lgkmcnt(0)
	s_lshl_b32 s51, s33, 12
	s_add_i32 s51, s51, s66
	s_lshl_b32 s52, s32, 10
	s_add_i32 s51, s51, s52
	s_add_i32 s51, s51, 0x3500000
	s_add_u32 s100, s98, s51
	s_addc_u32 s101, s99, 0
	s_add_u32 s70, s98, 0x3600000
	s_addc_u32 s71, s99, 0
	s_lshl_b32 s51, s33, 8
	s_lshl_b32 s52, s32, 6
	s_add_i32 s51, s51, s52
	s_add_i32 s51, s51, 0xf400000
	s_add_u32 s86, s98, s51
	s_addc_u32 s87, s99, 0
	v_add_u32_e32 v174, s89, v170
	v_add_u32_e32 v176, 0, v174
	v_cmp_gt_u32_e64 s[52:53], s91, v176
	s_nop 1
	v_cndmask_b32_e64 v176, 0, v176, s[52:53]
	v_add_u32_e32 v176, s88, v176
	v_lshl_add_u32 v248, v176, 6, v171
	global_load_dwordx4 v[222:225], v248, s[70:71]
	v_add_u32_e32 v176, 1, v174
	v_cmp_gt_u32_e64 s[64:65], s91, v176
	s_nop 1
	v_cndmask_b32_e64 v176, 0, v176, s[64:65]
	v_add_u32_e32 v176, s88, v176
	v_lshl_add_u32 v249, v176, 6, v171
	global_load_dwordx4 v[226:229], v249, s[70:71]
	v_add_u32_e32 v176, 2, v174
	v_cmp_gt_u32_e64 s[98:99], s91, v176
	s_nop 1
	v_cndmask_b32_e64 v176, 0, v176, s[98:99]
	v_add_u32_e32 v176, s88, v176
	v_lshl_add_u32 v250, v176, 6, v171
	global_load_dwordx4 v[230:233], v250, s[70:71]
	v_add_u32_e32 v176, 3, v174
	v_cmp_gt_u32_e64 s[32:33], s91, v176
	s_nop 1
	v_cndmask_b32_e64 v176, 0, v176, s[32:33]
	v_add_u32_e32 v176, s88, v176
	v_lshl_add_u32 v251, v176, 6, v171
	global_load_dwordx4 v[234:237], v251, s[70:71]
	global_load_dwordx4 v[190:193], v172, s[100:101]
	global_load_dwordx4 v[194:197], v172, s[100:101] offset:16
	global_load_dwordx4 v[198:201], v172, s[100:101] offset:32
	global_load_dwordx4 v[202:205], v172, s[100:101] offset:48
	s_waitcnt vmcnt(7)
	v_add_f32_e32 v222, v222, v223
	v_add_f32_e32 v224, v224, v225
	v_add_f32_e32 v222, v222, v224
	v_mov_b32_e32 v223, v222
	s_nop 1
	v_permlane16_swap_b32_e32 v222, v223
	v_add_f32_e32 v222, v222, v223
	v_mov_b32_e32 v223, v222
	s_nop 1
	v_permlane32_swap_b32_e32 v222, v223
	v_add_f32_e32 v222, v222, v223
	v_fma_f32 v222, v222, s82, v252
	v_rsq_f32_e32 v222, v222
	s_nop 0
	v_cndmask_b32_e64 v178, 0, v222, s[52:53]
	s_waitcnt vmcnt(6)
	v_add_f32_e32 v226, v226, v227
	v_add_f32_e32 v228, v228, v229
	v_add_f32_e32 v226, v226, v228
	v_mov_b32_e32 v227, v226
	s_nop 1
	v_permlane16_swap_b32_e32 v226, v227
	v_add_f32_e32 v226, v226, v227
	v_mov_b32_e32 v227, v226
	s_nop 1
	v_permlane32_swap_b32_e32 v226, v227
	v_add_f32_e32 v226, v226, v227
	v_fma_f32 v226, v226, s82, v252
	v_rsq_f32_e32 v226, v226
	s_nop 0
	v_cndmask_b32_e64 v180, 0, v226, s[64:65]
	s_waitcnt vmcnt(5)
	v_add_f32_e32 v230, v230, v231
	v_add_f32_e32 v232, v232, v233
	v_add_f32_e32 v230, v230, v232
	v_mov_b32_e32 v231, v230
	s_nop 1
	v_permlane16_swap_b32_e32 v230, v231
	v_add_f32_e32 v230, v230, v231
	v_mov_b32_e32 v231, v230
	s_nop 1
	v_permlane32_swap_b32_e32 v230, v231
	v_add_f32_e32 v230, v230, v231
	v_fma_f32 v230, v230, s82, v252
	v_rsq_f32_e32 v230, v230
	s_nop 0
	v_cndmask_b32_e64 v182, 0, v230, s[98:99]
	s_waitcnt vmcnt(4)
	v_add_f32_e32 v234, v234, v235
	v_add_f32_e32 v236, v236, v237
	v_add_f32_e32 v234, v234, v236
	v_mov_b32_e32 v235, v234
	s_nop 1
	v_permlane16_swap_b32_e32 v234, v235
	v_add_f32_e32 v234, v234, v235
	v_mov_b32_e32 v235, v234
	s_nop 1
	v_permlane32_swap_b32_e32 v234, v235
	v_add_f32_e32 v234, v234, v235
	v_fma_f32 v234, v234, s82, v252
	v_rsq_f32_e32 v234, v234
	s_nop 0
	v_cndmask_b32_e64 v144, 0, v234, s[32:33]
	global_load_dwordx4 v[206:209], v172, s[100:101] offset:64
	global_load_dwordx4 v[210:213], v172, s[100:101] offset:80
	global_load_dwordx4 v[214:217], v172, s[100:101] offset:96
	global_load_dwordx4 v[218:221], v172, s[100:101] offset:112
	s_waitcnt vmcnt(4)
	v_pk_mul_f32 v[124:125], v[124:125], v[178:179] op_sel_hi:[1,0]
	v_pk_mul_f32 v[120:121], v[120:121], v[180:181] op_sel_hi:[1,0]
	v_pk_mul_f32 v[116:117], v[116:117], v[182:183] op_sel_hi:[1,0]
	v_pk_mul_f32 v[112:113], v[112:113], v[144:145] op_sel_hi:[1,0]
	v_pk_mul_f32 v[108:109], v[108:109], v[178:179] op_sel_hi:[1,0]
	v_pk_mul_f32 v[104:105], v[104:105], v[180:181] op_sel_hi:[1,0]
	v_pk_mul_f32 v[100:101], v[100:101], v[182:183] op_sel_hi:[1,0]
	v_pk_mul_f32 v[96:97], v[96:97], v[144:145] op_sel_hi:[1,0]
	s_nop 1
	v_mov_b32_dpp v248, v112 row_shr:1 row_mask:0xf bank_mask:0xf bound_ctrl:1
	v_mov_b32_dpp v249, v113 row_shr:1 row_mask:0xf bank_mask:0xf bound_ctrl:1
	v_mov_b32_dpp v250, v124 row_shl:1 row_mask:0xf bank_mask:0xf bound_ctrl:1
	v_mov_b32_dpp v251, v125 row_shl:1 row_mask:0xf bank_mask:0xf bound_ctrl:1
	v_pk_fma_f32 v[224:225], v[190:191], v[248:249], v[196:197]
	v_pk_fma_f32 v[226:227], v[190:191], v[124:125], v[196:197]
	v_pk_fma_f32 v[228:229], v[190:191], v[120:121], v[196:197]
	v_pk_fma_f32 v[230:231], v[190:191], v[116:117], v[196:197]
	v_pk_fma_f32 v[224:225], v[192:193], v[124:125], v[224:225]
	v_pk_fma_f32 v[226:227], v[192:193], v[120:121], v[226:227]
	v_pk_fma_f32 v[228:229], v[192:193], v[116:117], v[228:229]
	v_pk_fma_f32 v[230:231], v[192:193], v[112:113], v[230:231]
	v_pk_fma_f32 v[224:225], v[194:195], v[120:121], v[224:225]
	v_pk_fma_f32 v[226:227], v[194:195], v[116:117], v[226:227]
; __device__ __forceinline__ unsigned cvtpk(float lo, float hi) { f32x2 v = {lo, hi}; bf16x2_t b = __builtin_convertvector(v, bf16x2_t); return __builtin_bit_cast(unsigned, b); }
; __device__ __forceinline__ float dpp_ror1(float x) { return __builtin_bit_cast(float, __builtin_amdgcn_mov_dpp(__builtin_bit_cast(int, x), 0x121, 0xF, 0xF, true)); }
; __device__ __forceinline__ float dpp_ror15(float x) { return __builtin_bit_cast(float, __builtin_amdgcn_mov_dpp(__builtin_bit_cast(int, x), 0x12F, 0xF, 0xF, true)); }
;     __device__ __forceinline__ void operator()(const f32x4 (&acc)[2][2][4][2], const Unit& u, int wr, int wc, int fr, int fq) const {
;     ...
;                         for (int m = 0; m < 4; ++m) { uv[m] = uv[m] * rs[m]; rv[m] = (f32x2){dpp_ror1(uv[m][0]), dpp_ror1(uv[m][1])}; lv[m] = (f32x2){dpp_ror15(uv[m][0]), dpp_ror15(uv[m][1])}; }
; #pragma unroll
;                         for (int m = 0; m < 4; ++m) { const f32x2 pv_ = (m > 0 && f0) ? rv[m > 0 ? m - 1 : 0] : rv[m], nv_ = (m < 3 && f15) ? lv[m < 3 ? m + 1 : 3] : lv[m];
;                             cv[m] = bv + wv0 * pv_ + wv1 * uv[m] + wv2 * nv_; }
;                     }
;                     asm volatile("" : "+v"(cv[0]), "+v"(cv[1]), "+v"(cv[2]), "+v"(cv[3]));
;                     {
;                         f32x2 rg[4], lg[4];
; #pragma unroll
;                         for (int m = 0; m < 4; ++m) { ug[m] = ug[m] * rs[m]; rg[m] = (f32x2){dpp_ror1(ug[m][0]), dpp_ror1(ug[m][1])}; lg[m] = (f32x2){dpp_ror15(ug[m][0]), dpp_ror15(ug[m][1])}; }
; #pragma unroll
;                         for (int m = 0; m < 4; ++m) { const f32x2 pg_ = (m > 0 && f0) ? rg[m > 0 ? m - 1 : 0] : rg[m], ng_ = (m < 3 && f15) ? lg[m < 3 ? m + 1 : 3] : lg[m];
;                             const f32x2 cgt = bg + wg0 * pg_ + wg1 * ug[m] + wg2 * ng_;
;                             const f32x2 e = cgt * (-LOG2E);
;                             const f32x2 d = (f32x2){__builtin_amdgcn_exp2f(e[0]), __builtin_amdgcn_exp2f(e[1])} + 1.f;
;                             const f32x2 sg = {__builtin_amdgcn_rcpf(d[0]), __builtin_amdgcn_rcpf(d[1])};
;                             const f32x2 ov = cv[m] * cgt * sg;
;                             outw[m][n][jp] = cvtpk(ov[0], ov[1]); }
	v_pk_fma_f32 v[228:229], v[194:195], v[112:113], v[228:229]
	v_pk_fma_f32 v[230:231], v[194:195], v[250:251], v[230:231]
	s_nop 1
	v_mov_b32_dpp v248, v96 row_shr:1 row_mask:0xf bank_mask:0xf bound_ctrl:1
	v_mov_b32_dpp v249, v97 row_shr:1 row_mask:0xf bank_mask:0xf bound_ctrl:1
	v_mov_b32_dpp v250, v108 row_shl:1 row_mask:0xf bank_mask:0xf bound_ctrl:1
	v_mov_b32_dpp v251, v109 row_shl:1 row_mask:0xf bank_mask:0xf bound_ctrl:1
	v_pk_fma_f32 v[232:233], v[198:199], v[248:249], v[204:205]
	v_pk_fma_f32 v[234:235], v[198:199], v[108:109], v[204:205]
	v_pk_fma_f32 v[236:237], v[198:199], v[104:105], v[204:205]
	v_pk_fma_f32 v[238:239], v[198:199], v[100:101], v[204:205]
	v_pk_fma_f32 v[232:233], v[200:201], v[108:109], v[232:233]
	v_pk_fma_f32 v[234:235], v[200:201], v[104:105], v[234:235]
	v_pk_fma_f32 v[236:237], v[200:201], v[100:101], v[236:237]
	v_pk_fma_f32 v[238:239], v[200:201], v[96:97], v[238:239]
	v_pk_fma_f32 v[232:233], v[202:203], v[104:105], v[232:233]
	v_pk_fma_f32 v[234:235], v[202:203], v[100:101], v[234:235]
	v_pk_fma_f32 v[236:237], v[202:203], v[96:97], v[236:237]
	v_pk_fma_f32 v[238:239], v[202:203], v[250:251], v[238:239]
	v_exp_f32_e64 v240, -v232
	v_exp_f32_e64 v241, -v233
	v_exp_f32_e64 v242, -v234
	v_exp_f32_e64 v243, -v235
	v_exp_f32_e64 v244, -v236
	v_exp_f32_e64 v245, -v237
	v_exp_f32_e64 v246, -v238
	v_exp_f32_e64 v247, -v239
	v_pk_mul_f32 v[224:225], v[224:225], v[232:233]
	v_pk_mul_f32 v[226:227], v[226:227], v[234:235]
	v_pk_mul_f32 v[228:229], v[228:229], v[236:237]
	v_pk_mul_f32 v[230:231], v[230:231], v[238:239]
	v_pk_add_f32 v[240:241], v[240:241], 1.0 op_sel_hi:[1,0]
	v_pk_add_f32 v[242:243], v[242:243], 1.0 op_sel_hi:[1,0]
	v_pk_add_f32 v[244:245], v[244:245], 1.0 op_sel_hi:[1,0]
	v_pk_add_f32 v[246:247], v[246:247], 1.0 op_sel_hi:[1,0]
	v_rcp_f32_e32 v240, v240
	v_rcp_f32_e32 v241, v241
	v_rcp_f32_e32 v242, v242
	v_rcp_f32_e32 v243, v243
	v_rcp_f32_e32 v244, v244
	v_rcp_f32_e32 v245, v245
	v_rcp_f32_e32 v246, v246
	v_rcp_f32_e32 v247, v247
	s_nop 0
	v_pk_mul_f32 v[224:225], v[224:225], v[240:241]
	v_pk_mul_f32 v[226:227], v[226:227], v[242:243]
	v_pk_mul_f32 v[228:229], v[228:229], v[244:245]
	v_pk_mul_f32 v[230:231], v[230:231], v[246:247]
	v_cvt_pk_bf16_f32 v128, v224, v225
	v_cvt_pk_bf16_f32 v132, v226, v227
	v_cvt_pk_bf16_f32 v136, v228, v229
	v_cvt_pk_bf16_f32 v140, v230, v231
	global_load_dwordx4 v[190:193], v172, s[100:101] offset:128
	global_load_dwordx4 v[194:197], v172, s[100:101] offset:144
	global_load_dwordx4 v[198:201], v172, s[100:101] offset:160
	global_load_dwordx4 v[202:205], v172, s[100:101] offset:176
	s_waitcnt vmcnt(4)
	v_pk_mul_f32 v[126:127], v[126:127], v[178:179] op_sel_hi:[1,0]
	v_pk_mul_f32 v[122:123], v[122:123], v[180:181] op_sel_hi:[1,0]
	v_pk_mul_f32 v[118:119], v[118:119], v[182:183] op_sel_hi:[1,0]
	v_pk_mul_f32 v[114:115], v[114:115], v[144:145] op_sel_hi:[1,0]
	v_pk_mul_f32 v[110:111], v[110:111], v[178:179] op_sel_hi:[1,0]
	v_pk_mul_f32 v[106:107], v[106:107], v[180:181] op_sel_hi:[1,0]
	v_pk_mul_f32 v[102:103], v[102:103], v[182:183] op_sel_hi:[1,0]
	v_pk_mul_f32 v[98:99], v[98:99], v[144:145] op_sel_hi:[1,0]
	s_nop 1
	v_mov_b32_dpp v248, v114 row_shr:1 row_mask:0xf bank_mask:0xf bound_ctrl:1
	v_mov_b32_dpp v249, v115 row_shr:1 row_mask:0xf bank_mask:0xf bound_ctrl:1
	v_mov_b32_dpp v250, v126 row_shl:1 row_mask:0xf bank_mask:0xf bound_ctrl:1
	v_mov_b32_dpp v251, v127 row_shl:1 row_mask:0xf bank_mask:0xf bound_ctrl:1
	v_pk_fma_f32 v[224:225], v[206:207], v[248:249], v[212:213]
	v_pk_fma_f32 v[226:227], v[206:207], v[126:127], v[212:213]
	v_pk_fma_f32 v[228:229], v[206:207], v[122:123], v[212:213]
	v_pk_fma_f32 v[230:231], v[206:207], v[118:119], v[212:213]
	v_pk_fma_f32 v[224:225], v[208:209], v[126:127], v[224:225]
	v_pk_fma_f32 v[226:227], v[208:209], v[122:123], v[226:227]
	v_pk_fma_f32 v[228:229], v[208:209], v[118:119], v[228:229]
	v_pk_fma_f32 v[230:231], v[208:209], v[114:115], v[230:231]
	v_pk_fma_f32 v[224:225], v[210:211], v[122:123], v[224:225]
	v_pk_fma_f32 v[226:227], v[210:211], v[118:119], v[226:227]
	v_pk_fma_f32 v[228:229], v[210:211], v[114:115], v[228:229]
	v_pk_fma_f32 v[230:231], v[210:211], v[250:251], v[230:231]
	s_nop 1
	v_mov_b32_dpp v248, v98 row_shr:1 row_mask:0xf bank_mask:0xf bound_ctrl:1
	v_mov_b32_dpp v249, v99 row_shr:1 row_mask:0xf bank_mask:0xf bound_ctrl:1
	v_mov_b32_dpp v250, v110 row_shl:1 row_mask:0xf bank_mask:0xf bound_ctrl:1
	v_mov_b32_dpp v251, v111 row_shl:1 row_mask:0xf bank_mask:0xf bound_ctrl:1
	v_pk_fma_f32 v[232:233], v[214:215], v[248:249], v[220:221]
	v_pk_fma_f32 v[234:235], v[214:215], v[110:111], v[220:221]
	v_pk_fma_f32 v[236:237], v[214:215], v[106:107], v[220:221]
	v_pk_fma_f32 v[238:239], v[214:215], v[102:103], v[220:221]
	v_pk_fma_f32 v[232:233], v[216:217], v[110:111], v[232:233]
	v_pk_fma_f32 v[234:235], v[216:217], v[106:107], v[234:235]
	v_pk_fma_f32 v[236:237], v[216:217], v[102:103], v[236:237]
	v_pk_fma_f32 v[238:239], v[216:217], v[98:99], v[238:239]
	v_pk_fma_f32 v[232:233], v[218:219], v[106:107], v[232:233]
	v_pk_fma_f32 v[234:235], v[218:219], v[102:103], v[234:235]
	v_pk_fma_f32 v[236:237], v[218:219], v[98:99], v[236:237]
	v_pk_fma_f32 v[238:239], v[218:219], v[250:251], v[238:239]
	v_exp_f32_e64 v240, -v232
	v_exp_f32_e64 v241, -v233
	v_exp_f32_e64 v242, -v234
	v_exp_f32_e64 v243, -v235
	v_exp_f32_e64 v244, -v236
	v_exp_f32_e64 v245, -v237
	v_exp_f32_e64 v246, -v238
	v_exp_f32_e64 v247, -v239
	v_pk_mul_f32 v[224:225], v[224:225], v[232:233]
	v_pk_mul_f32 v[226:227], v[226:227], v[234:235]
	v_pk_mul_f32 v[228:229], v[228:229], v[236:237]
	v_pk_mul_f32 v[230:231], v[230:231], v[238:239]
	v_pk_add_f32 v[240:241], v[240:241], 1.0 op_sel_hi:[1,0]
	v_pk_add_f32 v[242:243], v[242:243], 1.0 op_sel_hi:[1,0]
	v_pk_add_f32 v[244:245], v[244:245], 1.0 op_sel_hi:[1,0]
	v_pk_add_f32 v[246:247], v[246:247], 1.0 op_sel_hi:[1,0]
	v_rcp_f32_e32 v240, v240
	v_rcp_f32_e32 v241, v241
	v_rcp_f32_e32 v242, v242
	v_rcp_f32_e32 v243, v243
	v_rcp_f32_e32 v244, v244
	v_rcp_f32_e32 v245, v245
	v_rcp_f32_e32 v246, v246
	v_rcp_f32_e32 v247, v247
	s_nop 0
	v_pk_mul_f32 v[224:225], v[224:225], v[240:241]
	v_pk_mul_f32 v[226:227], v[226:227], v[242:243]
	v_pk_mul_f32 v[228:229], v[228:229], v[244:245]
	v_pk_mul_f32 v[230:231], v[230:231], v[246:247]
	v_cvt_pk_bf16_f32 v129, v224, v225
	v_cvt_pk_bf16_f32 v133, v226, v227
	v_cvt_pk_bf16_f32 v137, v228, v229
	v_cvt_pk_bf16_f32 v141, v230, v231
	global_load_dwordx4 v[206:209], v172, s[100:101] offset:192
	global_load_dwordx4 v[210:213], v172, s[100:101] offset:208
	global_load_dwordx4 v[214:217], v172, s[100:101] offset:224
	global_load_dwordx4 v[218:221], v172, s[100:101] offset:240
	s_waitcnt vmcnt(4)
; __device__ __forceinline__ unsigned cvtpk(float lo, float hi) { f32x2 v = {lo, hi}; bf16x2_t b = __builtin_convertvector(v, bf16x2_t); return __builtin_bit_cast(unsigned, b); }
; __device__ __forceinline__ float dpp_ror1(float x) { return __builtin_bit_cast(float, __builtin_amdgcn_mov_dpp(__builtin_bit_cast(int, x), 0x121, 0xF, 0xF, true)); }
; __device__ __forceinline__ float dpp_ror15(float x) { return __builtin_bit_cast(float, __builtin_amdgcn_mov_dpp(__builtin_bit_cast(int, x), 0x12F, 0xF, 0xF, true)); }
;     __device__ __forceinline__ void operator()(const f32x4 (&acc)[2][2][4][2], const Unit& u, int wr, int wc, int fr, int fq) const {
;     ...
;                         for (int m = 0; m < 4; ++m) { uv[m] = uv[m] * rs[m]; rv[m] = (f32x2){dpp_ror1(uv[m][0]), dpp_ror1(uv[m][1])}; lv[m] = (f32x2){dpp_ror15(uv[m][0]), dpp_ror15(uv[m][1])}; }
; #pragma unroll
;                         for (int m = 0; m < 4; ++m) { const f32x2 pv_ = (m > 0 && f0) ? rv[m > 0 ? m - 1 : 0] : rv[m], nv_ = (m < 3 && f15) ? lv[m < 3 ? m + 1 : 3] : lv[m];
;                             cv[m] = bv + wv0 * pv_ + wv1 * uv[m] + wv2 * nv_; }
;                     }
;                     asm volatile("" : "+v"(cv[0]), "+v"(cv[1]), "+v"(cv[2]), "+v"(cv[3]));
;                     {
;                         f32x2 rg[4], lg[4];
; #pragma unroll
;                         for (int m = 0; m < 4; ++m) { ug[m] = ug[m] * rs[m]; rg[m] = (f32x2){dpp_ror1(ug[m][0]), dpp_ror1(ug[m][1])}; lg[m] = (f32x2){dpp_ror15(ug[m][0]), dpp_ror15(ug[m][1])}; }
; #pragma unroll
;                         for (int m = 0; m < 4; ++m) { const f32x2 pg_ = (m > 0 && f0) ? rg[m > 0 ? m - 1 : 0] : rg[m], ng_ = (m < 3 && f15) ? lg[m < 3 ? m + 1 : 3] : lg[m];
;                             const f32x2 cgt = bg + wg0 * pg_ + wg1 * ug[m] + wg2 * ng_;
;                             const f32x2 e = cgt * (-LOG2E);
;                             const f32x2 d = (f32x2){__builtin_amdgcn_exp2f(e[0]), __builtin_amdgcn_exp2f(e[1])} + 1.f;
;                             const f32x2 sg = {__builtin_amdgcn_rcpf(d[0]), __builtin_amdgcn_rcpf(d[1])};
;                             const f32x2 ov = cv[m] * cgt * sg;
;                             outw[m][n][jp] = cvtpk(ov[0], ov[1]); }
	v_pk_mul_f32 v[92:93], v[92:93], v[178:179] op_sel_hi:[1,0]
	v_pk_mul_f32 v[88:89], v[88:89], v[180:181] op_sel_hi:[1,0]
	v_pk_mul_f32 v[84:85], v[84:85], v[182:183] op_sel_hi:[1,0]
	v_pk_mul_f32 v[80:81], v[80:81], v[144:145] op_sel_hi:[1,0]
	v_pk_mul_f32 v[76:77], v[76:77], v[178:179] op_sel_hi:[1,0]
	v_pk_mul_f32 v[72:73], v[72:73], v[180:181] op_sel_hi:[1,0]
	v_pk_mul_f32 v[68:69], v[68:69], v[182:183] op_sel_hi:[1,0]
	v_pk_mul_f32 v[64:65], v[64:65], v[144:145] op_sel_hi:[1,0]
	s_nop 1
	v_mov_b32_dpp v248, v80 row_shr:1 row_mask:0xf bank_mask:0xf bound_ctrl:1
	v_mov_b32_dpp v249, v81 row_shr:1 row_mask:0xf bank_mask:0xf bound_ctrl:1
	v_mov_b32_dpp v250, v92 row_shl:1 row_mask:0xf bank_mask:0xf bound_ctrl:1
	v_mov_b32_dpp v251, v93 row_shl:1 row_mask:0xf bank_mask:0xf bound_ctrl:1
	v_pk_fma_f32 v[224:225], v[190:191], v[248:249], v[196:197]
	v_pk_fma_f32 v[226:227], v[190:191], v[92:93], v[196:197]
	v_pk_fma_f32 v[228:229], v[190:191], v[88:89], v[196:197]
	v_pk_fma_f32 v[230:231], v[190:191], v[84:85], v[196:197]
	v_pk_fma_f32 v[224:225], v[192:193], v[92:93], v[224:225]
	v_pk_fma_f32 v[226:227], v[192:193], v[88:89], v[226:227]
	v_pk_fma_f32 v[228:229], v[192:193], v[84:85], v[228:229]
	v_pk_fma_f32 v[230:231], v[192:193], v[80:81], v[230:231]
	v_pk_fma_f32 v[224:225], v[194:195], v[88:89], v[224:225]
	v_pk_fma_f32 v[226:227], v[194:195], v[84:85], v[226:227]
	v_pk_fma_f32 v[228:229], v[194:195], v[80:81], v[228:229]
	v_pk_fma_f32 v[230:231], v[194:195], v[250:251], v[230:231]
	s_nop 1
	v_mov_b32_dpp v248, v64 row_shr:1 row_mask:0xf bank_mask:0xf bound_ctrl:1
	v_mov_b32_dpp v249, v65 row_shr:1 row_mask:0xf bank_mask:0xf bound_ctrl:1
	v_mov_b32_dpp v250, v76 row_shl:1 row_mask:0xf bank_mask:0xf bound_ctrl:1
	v_mov_b32_dpp v251, v77 row_shl:1 row_mask:0xf bank_mask:0xf bound_ctrl:1
	v_pk_fma_f32 v[232:233], v[198:199], v[248:249], v[204:205]
	v_pk_fma_f32 v[234:235], v[198:199], v[76:77], v[204:205]
	v_pk_fma_f32 v[236:237], v[198:199], v[72:73], v[204:205]
	v_pk_fma_f32 v[238:239], v[198:199], v[68:69], v[204:205]
	v_pk_fma_f32 v[232:233], v[200:201], v[76:77], v[232:233]
	v_pk_fma_f32 v[234:235], v[200:201], v[72:73], v[234:235]
	v_pk_fma_f32 v[236:237], v[200:201], v[68:69], v[236:237]
	v_pk_fma_f32 v[238:239], v[200:201], v[64:65], v[238:239]
	v_pk_fma_f32 v[232:233], v[202:203], v[72:73], v[232:233]
	v_pk_fma_f32 v[234:235], v[202:203], v[68:69], v[234:235]
	v_pk_fma_f32 v[236:237], v[202:203], v[64:65], v[236:237]
	v_pk_fma_f32 v[238:239], v[202:203], v[250:251], v[238:239]
	v_exp_f32_e64 v240, -v232
	v_exp_f32_e64 v241, -v233
	v_exp_f32_e64 v242, -v234
	v_exp_f32_e64 v243, -v235
	v_exp_f32_e64 v244, -v236
	v_exp_f32_e64 v245, -v237
	v_exp_f32_e64 v246, -v238
	v_exp_f32_e64 v247, -v239
	v_pk_mul_f32 v[224:225], v[224:225], v[232:233]
	v_pk_mul_f32 v[226:227], v[226:227], v[234:235]
	v_pk_mul_f32 v[228:229], v[228:229], v[236:237]
	v_pk_mul_f32 v[230:231], v[230:231], v[238:239]
	v_pk_add_f32 v[240:241], v[240:241], 1.0 op_sel_hi:[1,0]
	v_pk_add_f32 v[242:243], v[242:243], 1.0 op_sel_hi:[1,0]
	v_pk_add_f32 v[244:245], v[244:245], 1.0 op_sel_hi:[1,0]
	v_pk_add_f32 v[246:247], v[246:247], 1.0 op_sel_hi:[1,0]
	v_rcp_f32_e32 v240, v240
	v_rcp_f32_e32 v241, v241
	v_rcp_f32_e32 v242, v242
	v_rcp_f32_e32 v243, v243
	v_rcp_f32_e32 v244, v244
	v_rcp_f32_e32 v245, v245
	v_rcp_f32_e32 v246, v246
	v_rcp_f32_e32 v247, v247
	s_nop 0
	v_pk_mul_f32 v[224:225], v[224:225], v[240:241]
	v_pk_mul_f32 v[226:227], v[226:227], v[242:243]
	v_pk_mul_f32 v[228:229], v[228:229], v[244:245]
	v_pk_mul_f32 v[230:231], v[230:231], v[246:247]
	v_cvt_pk_bf16_f32 v130, v224, v225
	v_cvt_pk_bf16_f32 v134, v226, v227
	v_cvt_pk_bf16_f32 v138, v228, v229
	v_cvt_pk_bf16_f32 v142, v230, v231
	s_waitcnt vmcnt(0)
	v_pk_mul_f32 v[94:95], v[94:95], v[178:179] op_sel_hi:[1,0]
	v_pk_mul_f32 v[90:91], v[90:91], v[180:181] op_sel_hi:[1,0]
	v_pk_mul_f32 v[86:87], v[86:87], v[182:183] op_sel_hi:[1,0]
	v_pk_mul_f32 v[82:83], v[82:83], v[144:145] op_sel_hi:[1,0]
	v_pk_mul_f32 v[78:79], v[78:79], v[178:179] op_sel_hi:[1,0]
	v_pk_mul_f32 v[74:75], v[74:75], v[180:181] op_sel_hi:[1,0]
	v_pk_mul_f32 v[70:71], v[70:71], v[182:183] op_sel_hi:[1,0]
	v_pk_mul_f32 v[66:67], v[66:67], v[144:145] op_sel_hi:[1,0]
	s_nop 1
	v_mov_b32_dpp v248, v82 row_shr:1 row_mask:0xf bank_mask:0xf bound_ctrl:1
	v_mov_b32_dpp v249, v83 row_shr:1 row_mask:0xf bank_mask:0xf bound_ctrl:1
	v_mov_b32_dpp v250, v94 row_shl:1 row_mask:0xf bank_mask:0xf bound_ctrl:1
	v_mov_b32_dpp v251, v95 row_shl:1 row_mask:0xf bank_mask:0xf bound_ctrl:1
	v_pk_fma_f32 v[224:225], v[206:207], v[248:249], v[212:213]
	v_pk_fma_f32 v[226:227], v[206:207], v[94:95], v[212:213]
	v_pk_fma_f32 v[228:229], v[206:207], v[90:91], v[212:213]
	v_pk_fma_f32 v[230:231], v[206:207], v[86:87], v[212:213]
	v_pk_fma_f32 v[224:225], v[208:209], v[94:95], v[224:225]
	v_pk_fma_f32 v[226:227], v[208:209], v[90:91], v[226:227]
	v_pk_fma_f32 v[228:229], v[208:209], v[86:87], v[228:229]
	v_pk_fma_f32 v[230:231], v[208:209], v[82:83], v[230:231]
	v_pk_fma_f32 v[224:225], v[210:211], v[90:91], v[224:225]
	v_pk_fma_f32 v[226:227], v[210:211], v[86:87], v[226:227]
	v_pk_fma_f32 v[228:229], v[210:211], v[82:83], v[228:229]
	v_pk_fma_f32 v[230:231], v[210:211], v[250:251], v[230:231]
	s_nop 1
	v_mov_b32_dpp v248, v66 row_shr:1 row_mask:0xf bank_mask:0xf bound_ctrl:1
	v_mov_b32_dpp v249, v67 row_shr:1 row_mask:0xf bank_mask:0xf bound_ctrl:1
	v_mov_b32_dpp v250, v78 row_shl:1 row_mask:0xf bank_mask:0xf bound_ctrl:1
	v_mov_b32_dpp v251, v79 row_shl:1 row_mask:0xf bank_mask:0xf bound_ctrl:1
	v_pk_fma_f32 v[232:233], v[214:215], v[248:249], v[220:221]
; __device__ __forceinline__ unsigned cvtpk(float lo, float hi) { f32x2 v = {lo, hi}; bf16x2_t b = __builtin_convertvector(v, bf16x2_t); return __builtin_bit_cast(unsigned, b); }
;     __device__ __forceinline__ void operator()(const f32x4 (&acc)[2][2][4][2], const Unit& u, int wr, int wc, int fr, int fq) const {
;     ...
;             const int tbase = t0 + 62 * (2 * ai + wr) - 1;
;             float rs[4];
; #pragma unroll
;             for (int m = 0; m < 4; ++m) { const int t = tbase + 16 * m + fr; const bool vin = (t >= 0) && (t < slen); const int grow = seqbase + (vin ? t : 0);
;                 const f32x4 p = *(const f32x4*)(PS + (size_t)grow * 16 + 4 * fq); float s = (p[0] + p[1]) + (p[2] + p[3]); s = bfly_add<16>(s); s = bfly_add<32>(s); rs[m] = vin ? rsqrtf(s * (1.f / DM) + EPS) : 0.f; }
;     ...
;                         for (int m = 0; m < 4; ++m) { ug[m] = ug[m] * rs[m]; rg[m] = (f32x2){dpp_ror1(ug[m][0]), dpp_ror1(ug[m][1])}; lg[m] = (f32x2){dpp_ror15(ug[m][0]), dpp_ror15(ug[m][1])}; }
; #pragma unroll
;                         for (int m = 0; m < 4; ++m) { const f32x2 pg_ = (m > 0 && f0) ? rg[m > 0 ? m - 1 : 0] : rg[m], ng_ = (m < 3 && f15) ? lg[m < 3 ? m + 1 : 3] : lg[m];
;                             const f32x2 cgt = bg + wg0 * pg_ + wg1 * ug[m] + wg2 * ng_;
;                             const f32x2 e = cgt * (-LOG2E);
;                             const f32x2 d = (f32x2){__builtin_amdgcn_exp2f(e[0]), __builtin_amdgcn_exp2f(e[1])} + 1.f;
;                             const f32x2 sg = {__builtin_amdgcn_rcpf(d[0]), __builtin_amdgcn_rcpf(d[1])};
;                             const f32x2 ov = cv[m] * cgt * sg;
;                             outw[m][n][jp] = cvtpk(ov[0], ov[1]); }
;                     }
;                     asm volatile("" : "+v"(outw[0][n][jp]), "+v"(outw[1][n][jp]), "+v"(outw[2][n][jp]), "+v"(outw[3][n][jp]) :: "memory"); __builtin_amdgcn_sched_barrier(0);
;                 }
; #pragma unroll
;             for (int m = 0; m < 4; ++m) { const int i = 16 * m + fr, t = tbase + i;
;                 if (i >= 1 && i <= 62 && t < slen) { u32x4 w; w.x = outw[m][0][0]; w.y = outw[m][0][1]; w.z = outw[m][1][0]; w.w = outw[m][1][1];
;                     *(u32x4*)(Gout + (size_t)(seqbase + t) * DFF + 128 * u.pn + 32 * wc + 8 * fq) = w; } }
	v_pk_fma_f32 v[234:235], v[214:215], v[78:79], v[220:221]
	v_pk_fma_f32 v[236:237], v[214:215], v[74:75], v[220:221]
	v_pk_fma_f32 v[238:239], v[214:215], v[70:71], v[220:221]
	v_pk_fma_f32 v[232:233], v[216:217], v[78:79], v[232:233]
	v_pk_fma_f32 v[234:235], v[216:217], v[74:75], v[234:235]
	v_pk_fma_f32 v[236:237], v[216:217], v[70:71], v[236:237]
	v_pk_fma_f32 v[238:239], v[216:217], v[66:67], v[238:239]
	v_pk_fma_f32 v[232:233], v[218:219], v[74:75], v[232:233]
	v_pk_fma_f32 v[234:235], v[218:219], v[70:71], v[234:235]
	v_pk_fma_f32 v[236:237], v[218:219], v[66:67], v[236:237]
	v_pk_fma_f32 v[238:239], v[218:219], v[250:251], v[238:239]
	v_exp_f32_e64 v240, -v232
	v_exp_f32_e64 v241, -v233
	v_exp_f32_e64 v242, -v234
	v_exp_f32_e64 v243, -v235
	v_exp_f32_e64 v244, -v236
	v_exp_f32_e64 v245, -v237
	v_exp_f32_e64 v246, -v238
	v_exp_f32_e64 v247, -v239
	v_pk_mul_f32 v[224:225], v[224:225], v[232:233]
	v_pk_mul_f32 v[226:227], v[226:227], v[234:235]
	v_pk_mul_f32 v[228:229], v[228:229], v[236:237]
	v_pk_mul_f32 v[230:231], v[230:231], v[238:239]
	v_pk_add_f32 v[240:241], v[240:241], 1.0 op_sel_hi:[1,0]
	v_pk_add_f32 v[242:243], v[242:243], 1.0 op_sel_hi:[1,0]
	v_pk_add_f32 v[244:245], v[244:245], 1.0 op_sel_hi:[1,0]
	v_pk_add_f32 v[246:247], v[246:247], 1.0 op_sel_hi:[1,0]
	v_rcp_f32_e32 v240, v240
	v_rcp_f32_e32 v241, v241
	v_rcp_f32_e32 v242, v242
	v_rcp_f32_e32 v243, v243
	v_rcp_f32_e32 v244, v244
	v_rcp_f32_e32 v245, v245
	v_rcp_f32_e32 v246, v246
	v_rcp_f32_e32 v247, v247
	s_nop 0
	v_pk_mul_f32 v[224:225], v[224:225], v[240:241]
	v_pk_mul_f32 v[226:227], v[226:227], v[242:243]
	v_pk_mul_f32 v[228:229], v[228:229], v[244:245]
	v_pk_mul_f32 v[230:231], v[230:231], v[246:247]
	v_cvt_pk_bf16_f32 v131, v224, v225
	v_cvt_pk_bf16_f32 v135, v226, v227
	v_cvt_pk_bf16_f32 v139, v228, v229
	v_cvt_pk_bf16_f32 v143, v230, v231
	v_add_u32_e32 v176, 0, v174
	v_cmp_gt_u32_e32 vcc, s91, v176
	v_cmp_ne_u32_e64 s[52:53], 0, v170
	s_and_b64 vcc, vcc, s[52:53]
	v_add_u32_e32 v176, s88, v176
	v_mad_u32_u24 v248, v176, s54, v171
	s_and_saveexec_b64 s[64:65], vcc
	global_store_dwordx4 v248, v[128:131], s[86:87]
	s_mov_b64 exec, s[64:65]
	v_add_u32_e32 v176, 1, v174
	v_cmp_gt_u32_e32 vcc, s91, v176
	v_add_u32_e32 v176, s88, v176
	v_mad_u32_u24 v249, v176, s54, v171
	s_and_saveexec_b64 s[64:65], vcc
	global_store_dwordx4 v249, v[132:135], s[86:87]
	s_mov_b64 exec, s[64:65]
	v_add_u32_e32 v176, 2, v174
	v_cmp_gt_u32_e32 vcc, s91, v176
	v_add_u32_e32 v176, s88, v176
	v_mad_u32_u24 v250, v176, s54, v171
	s_and_saveexec_b64 s[64:65], vcc
	global_store_dwordx4 v250, v[136:139], s[86:87]
	s_mov_b64 exec, s[64:65]
	v_add_u32_e32 v176, 3, v174
	v_cmp_gt_u32_e32 vcc, s91, v176
	v_cmp_ne_u32_e64 s[52:53], 60, v170
	s_and_b64 vcc, vcc, s[52:53]
	v_add_u32_e32 v176, s88, v176
	v_mad_u32_u24 v251, v176, s54, v171
	s_and_saveexec_b64 s[64:65], vcc
	global_store_dwordx4 v251, v[140:143], s[86:87]
	s_mov_b64 exec, s[64:65]
	s_addk_i32 s89, 0x7c
	v_add_u32_e32 v174, s89, v170
	v_add_u32_e32 v176, 0, v174
	v_cmp_gt_u32_e64 s[52:53], s91, v176
	s_nop 1
	v_cndmask_b32_e64 v176, 0, v176, s[52:53]
	v_add_u32_e32 v176, s88, v176
	v_lshl_add_u32 v248, v176, 6, v171
	global_load_dwordx4 v[222:225], v248, s[70:71]
	v_add_u32_e32 v176, 1, v174
	v_cmp_gt_u32_e64 s[64:65], s91, v176
	s_nop 1
	v_cndmask_b32_e64 v176, 0, v176, s[64:65]
	v_add_u32_e32 v176, s88, v176
	v_lshl_add_u32 v249, v176, 6, v171
	global_load_dwordx4 v[226:229], v249, s[70:71]
	v_add_u32_e32 v176, 2, v174
	v_cmp_gt_u32_e64 s[98:99], s91, v176
	s_nop 1
	v_cndmask_b32_e64 v176, 0, v176, s[98:99]
	v_add_u32_e32 v176, s88, v176
	v_lshl_add_u32 v250, v176, 6, v171
	global_load_dwordx4 v[230:233], v250, s[70:71]
	v_add_u32_e32 v176, 3, v174
	v_cmp_gt_u32_e64 s[32:33], s91, v176
	s_nop 1
	v_cndmask_b32_e64 v176, 0, v176, s[32:33]
	v_add_u32_e32 v176, s88, v176
	v_lshl_add_u32 v251, v176, 6, v171
	global_load_dwordx4 v[234:237], v251, s[70:71]
	global_load_dwordx4 v[190:193], v172, s[100:101]
	global_load_dwordx4 v[194:197], v172, s[100:101] offset:16
	global_load_dwordx4 v[198:201], v172, s[100:101] offset:32
	global_load_dwordx4 v[202:205], v172, s[100:101] offset:48
	s_waitcnt vmcnt(7)
	v_add_f32_e32 v222, v222, v223
	v_add_f32_e32 v224, v224, v225
	v_add_f32_e32 v222, v222, v224
	v_mov_b32_e32 v223, v222
	s_nop 1
	v_permlane16_swap_b32_e32 v222, v223
	v_add_f32_e32 v222, v222, v223
	v_mov_b32_e32 v223, v222
	s_nop 1
	v_permlane32_swap_b32_e32 v222, v223
	v_add_f32_e32 v222, v222, v223
	v_fma_f32 v222, v222, s82, v252
	v_rsq_f32_e32 v222, v222
	s_nop 0
	v_cndmask_b32_e64 v178, 0, v222, s[52:53]
	s_waitcnt vmcnt(6)
	v_add_f32_e32 v226, v226, v227
	v_add_f32_e32 v228, v228, v229
	v_add_f32_e32 v226, v226, v228
	v_mov_b32_e32 v227, v226
	s_nop 1
	v_permlane16_swap_b32_e32 v226, v227
	v_add_f32_e32 v226, v226, v227
	v_mov_b32_e32 v227, v226
	s_nop 1
	v_permlane32_swap_b32_e32 v226, v227
	v_add_f32_e32 v226, v226, v227
	v_fma_f32 v226, v226, s82, v252
	v_rsq_f32_e32 v226, v226
	s_nop 0
	v_cndmask_b32_e64 v180, 0, v226, s[64:65]
	s_waitcnt vmcnt(5)
	v_add_f32_e32 v230, v230, v231
	v_add_f32_e32 v232, v232, v233
	v_add_f32_e32 v230, v230, v232
	v_mov_b32_e32 v231, v230
	s_nop 1
	v_permlane16_swap_b32_e32 v230, v231
	v_add_f32_e32 v230, v230, v231
	v_mov_b32_e32 v231, v230
	s_nop 1
	v_permlane32_swap_b32_e32 v230, v231
	v_add_f32_e32 v230, v230, v231
	v_fma_f32 v230, v230, s82, v252
	v_rsq_f32_e32 v230, v230
	s_nop 0
	v_cndmask_b32_e64 v182, 0, v230, s[98:99]
	s_waitcnt vmcnt(4)
; __device__ __forceinline__ float dpp_ror1(float x) { return __builtin_bit_cast(float, __builtin_amdgcn_mov_dpp(__builtin_bit_cast(int, x), 0x121, 0xF, 0xF, true)); }
;     __device__ __forceinline__ void operator()(const f32x4 (&acc)[2][2][4][2], const Unit& u, int wr, int wc, int fr, int fq) const {
;     ...
;             for (int m = 0; m < 4; ++m) { const int t = tbase + 16 * m + fr; const bool vin = (t >= 0) && (t < slen); const int grow = seqbase + (vin ? t : 0);
;                 const f32x4 p = *(const f32x4*)(PS + (size_t)grow * 16 + 4 * fq); float s = (p[0] + p[1]) + (p[2] + p[3]); s = bfly_add<16>(s); s = bfly_add<32>(s); rs[m] = vin ? rsqrtf(s * (1.f / DM) + EPS) : 0.f; }
;             unsigned outw[4][2][2];
; #pragma unroll
;             for (int n = 0; n < 2; ++n)
; #pragma unroll
;                 for (int jp = 0; jp < 2; ++jp) {
;                     const int cidx = (4 * n + 2 * jp) * 2;
;                     const f32x4 c0a = ct[cidx], c0b = ct[cidx + 1], c1a = ct[cidx + 2], c1b = ct[cidx + 3];
;                     const f32x2 wv0 = {c0a[0], c1a[0]}, wv1 = {c0a[1], c1a[1]}, wv2 = {c0a[2], c1a[2]}, bv = {c0a[3], c1a[3]};
;                     const f32x2 wg0 = {c0b[0], c1b[0]}, wg1 = {c0b[1], c1b[1]}, wg2 = {c0b[2], c1b[2]}, bg = {c0b[3], c1b[3]};
;                     f32x2 uv[4], ug[4], cv[4];
; #pragma unroll
;                     for (int m = 0; m < 4; ++m) { uv[m] = (f32x2){acc[ai][0][m][n][2 * jp], acc[ai][0][m][n][2 * jp + 1]}; ug[m] = (f32x2){acc[ai][1][m][n][2 * jp], acc[ai][1][m][n][2 * jp + 1]}; }
;                     asm volatile("" : "+v"(uv[0]), "+v"(uv[1]), "+v"(uv[2]), "+v"(uv[3]), "+v"(ug[0]), "+v"(ug[1]), "+v"(ug[2]), "+v"(ug[3]));
;                     {
;                         f32x2 rv[4], lv[4];
; #pragma unroll
;                         for (int m = 0; m < 4; ++m) { uv[m] = uv[m] * rs[m]; rv[m] = (f32x2){dpp_ror1(uv[m][0]), dpp_ror1(uv[m][1])}; lv[m] = (f32x2){dpp_ror15(uv[m][0]), dpp_ror15(uv[m][1])}; }
; #pragma unroll
;                         for (int m = 0; m < 4; ++m) { const f32x2 pv_ = (m > 0 && f0) ? rv[m > 0 ? m - 1 : 0] : rv[m], nv_ = (m < 3 && f15) ? lv[m < 3 ? m + 1 : 3] : lv[m];
;                             cv[m] = bv + wv0 * pv_ + wv1 * uv[m] + wv2 * nv_; }
	v_add_f32_e32 v234, v234, v235
	v_add_f32_e32 v236, v236, v237
	v_add_f32_e32 v234, v234, v236
	v_mov_b32_e32 v235, v234
	s_nop 1
	v_permlane16_swap_b32_e32 v234, v235
	v_add_f32_e32 v234, v234, v235
	v_mov_b32_e32 v235, v234
	s_nop 1
	v_permlane32_swap_b32_e32 v234, v235
	v_add_f32_e32 v234, v234, v235
	v_fma_f32 v234, v234, s82, v252
	v_rsq_f32_e32 v234, v234
	s_nop 0
	v_cndmask_b32_e64 v144, 0, v234, s[32:33]
	global_load_dwordx4 v[206:209], v172, s[100:101] offset:64
	global_load_dwordx4 v[210:213], v172, s[100:101] offset:80
	global_load_dwordx4 v[214:217], v172, s[100:101] offset:96
	global_load_dwordx4 v[218:221], v172, s[100:101] offset:112
	s_waitcnt vmcnt(4)
	v_pk_mul_f32 v[60:61], v[60:61], v[178:179] op_sel_hi:[1,0]
	v_pk_mul_f32 v[56:57], v[56:57], v[180:181] op_sel_hi:[1,0]
	v_pk_mul_f32 v[52:53], v[52:53], v[182:183] op_sel_hi:[1,0]
	v_pk_mul_f32 v[48:49], v[48:49], v[144:145] op_sel_hi:[1,0]
	v_pk_mul_f32 v[44:45], v[44:45], v[178:179] op_sel_hi:[1,0]
	v_pk_mul_f32 v[40:41], v[40:41], v[180:181] op_sel_hi:[1,0]
	v_pk_mul_f32 v[36:37], v[36:37], v[182:183] op_sel_hi:[1,0]
	v_pk_mul_f32 v[32:33], v[32:33], v[144:145] op_sel_hi:[1,0]
	s_nop 1
	v_mov_b32_dpp v248, v48 row_shr:1 row_mask:0xf bank_mask:0xf bound_ctrl:1
	v_mov_b32_dpp v249, v49 row_shr:1 row_mask:0xf bank_mask:0xf bound_ctrl:1
	v_mov_b32_dpp v250, v60 row_shl:1 row_mask:0xf bank_mask:0xf bound_ctrl:1
	v_mov_b32_dpp v251, v61 row_shl:1 row_mask:0xf bank_mask:0xf bound_ctrl:1
	v_pk_fma_f32 v[224:225], v[190:191], v[248:249], v[196:197]
	v_pk_fma_f32 v[226:227], v[190:191], v[60:61], v[196:197]
	v_pk_fma_f32 v[228:229], v[190:191], v[56:57], v[196:197]
	v_pk_fma_f32 v[230:231], v[190:191], v[52:53], v[196:197]
	v_pk_fma_f32 v[224:225], v[192:193], v[60:61], v[224:225]
	v_pk_fma_f32 v[226:227], v[192:193], v[56:57], v[226:227]
	v_pk_fma_f32 v[228:229], v[192:193], v[52:53], v[228:229]
	v_pk_fma_f32 v[230:231], v[192:193], v[48:49], v[230:231]
	v_pk_fma_f32 v[224:225], v[194:195], v[56:57], v[224:225]
	v_pk_fma_f32 v[226:227], v[194:195], v[52:53], v[226:227]
	v_pk_fma_f32 v[228:229], v[194:195], v[48:49], v[228:229]
	v_pk_fma_f32 v[230:231], v[194:195], v[250:251], v[230:231]
	s_nop 1
	v_mov_b32_dpp v248, v32 row_shr:1 row_mask:0xf bank_mask:0xf bound_ctrl:1
	v_mov_b32_dpp v249, v33 row_shr:1 row_mask:0xf bank_mask:0xf bound_ctrl:1
	v_mov_b32_dpp v250, v44 row_shl:1 row_mask:0xf bank_mask:0xf bound_ctrl:1
	v_mov_b32_dpp v251, v45 row_shl:1 row_mask:0xf bank_mask:0xf bound_ctrl:1
	v_pk_fma_f32 v[232:233], v[198:199], v[248:249], v[204:205]
	v_pk_fma_f32 v[234:235], v[198:199], v[44:45], v[204:205]
	v_pk_fma_f32 v[236:237], v[198:199], v[40:41], v[204:205]
	v_pk_fma_f32 v[238:239], v[198:199], v[36:37], v[204:205]
	v_pk_fma_f32 v[232:233], v[200:201], v[44:45], v[232:233]
	v_pk_fma_f32 v[234:235], v[200:201], v[40:41], v[234:235]
	v_pk_fma_f32 v[236:237], v[200:201], v[36:37], v[236:237]
	v_pk_fma_f32 v[238:239], v[200:201], v[32:33], v[238:239]
	v_pk_fma_f32 v[232:233], v[202:203], v[40:41], v[232:233]
	v_pk_fma_f32 v[234:235], v[202:203], v[36:37], v[234:235]
	v_pk_fma_f32 v[236:237], v[202:203], v[32:33], v[236:237]
	v_pk_fma_f32 v[238:239], v[202:203], v[250:251], v[238:239]
	v_exp_f32_e64 v240, -v232
	v_exp_f32_e64 v241, -v233
	v_exp_f32_e64 v242, -v234
	v_exp_f32_e64 v243, -v235
	v_exp_f32_e64 v244, -v236
	v_exp_f32_e64 v245, -v237
	v_exp_f32_e64 v246, -v238
	v_exp_f32_e64 v247, -v239
	v_pk_mul_f32 v[224:225], v[224:225], v[232:233]
	v_pk_mul_f32 v[226:227], v[226:227], v[234:235]
	v_pk_mul_f32 v[228:229], v[228:229], v[236:237]
	v_pk_mul_f32 v[230:231], v[230:231], v[238:239]
	v_pk_add_f32 v[240:241], v[240:241], 1.0 op_sel_hi:[1,0]
	v_pk_add_f32 v[242:243], v[242:243], 1.0 op_sel_hi:[1,0]
	v_pk_add_f32 v[244:245], v[244:245], 1.0 op_sel_hi:[1,0]
	v_pk_add_f32 v[246:247], v[246:247], 1.0 op_sel_hi:[1,0]
	v_rcp_f32_e32 v240, v240
	v_rcp_f32_e32 v241, v241
	v_rcp_f32_e32 v242, v242
	v_rcp_f32_e32 v243, v243
	v_rcp_f32_e32 v244, v244
	v_rcp_f32_e32 v245, v245
	v_rcp_f32_e32 v246, v246
	v_rcp_f32_e32 v247, v247
	s_nop 0
	v_pk_mul_f32 v[224:225], v[224:225], v[240:241]
	v_pk_mul_f32 v[226:227], v[226:227], v[242:243]
	v_pk_mul_f32 v[228:229], v[228:229], v[244:245]
	v_pk_mul_f32 v[230:231], v[230:231], v[246:247]
	v_cvt_pk_bf16_f32 v128, v224, v225
	v_cvt_pk_bf16_f32 v132, v226, v227
	v_cvt_pk_bf16_f32 v136, v228, v229
	v_cvt_pk_bf16_f32 v140, v230, v231
	global_load_dwordx4 v[190:193], v172, s[100:101] offset:128
	global_load_dwordx4 v[194:197], v172, s[100:101] offset:144
	global_load_dwordx4 v[198:201], v172, s[100:101] offset:160
	global_load_dwordx4 v[202:205], v172, s[100:101] offset:176
	s_waitcnt vmcnt(4)
; __device__ __forceinline__ unsigned cvtpk(float lo, float hi) { f32x2 v = {lo, hi}; bf16x2_t b = __builtin_convertvector(v, bf16x2_t); return __builtin_bit_cast(unsigned, b); }
; __device__ __forceinline__ float dpp_ror1(float x) { return __builtin_bit_cast(float, __builtin_amdgcn_mov_dpp(__builtin_bit_cast(int, x), 0x121, 0xF, 0xF, true)); }
; __device__ __forceinline__ float dpp_ror15(float x) { return __builtin_bit_cast(float, __builtin_amdgcn_mov_dpp(__builtin_bit_cast(int, x), 0x12F, 0xF, 0xF, true)); }
;     __device__ __forceinline__ void operator()(const f32x4 (&acc)[2][2][4][2], const Unit& u, int wr, int wc, int fr, int fq) const {
;     ...
;                         for (int m = 0; m < 4; ++m) { uv[m] = uv[m] * rs[m]; rv[m] = (f32x2){dpp_ror1(uv[m][0]), dpp_ror1(uv[m][1])}; lv[m] = (f32x2){dpp_ror15(uv[m][0]), dpp_ror15(uv[m][1])}; }
; #pragma unroll
;                         for (int m = 0; m < 4; ++m) { const f32x2 pv_ = (m > 0 && f0) ? rv[m > 0 ? m - 1 : 0] : rv[m], nv_ = (m < 3 && f15) ? lv[m < 3 ? m + 1 : 3] : lv[m];
;                             cv[m] = bv + wv0 * pv_ + wv1 * uv[m] + wv2 * nv_; }
;                     }
;                     asm volatile("" : "+v"(cv[0]), "+v"(cv[1]), "+v"(cv[2]), "+v"(cv[3]));
;                     {
;                         f32x2 rg[4], lg[4];
; #pragma unroll
;                         for (int m = 0; m < 4; ++m) { ug[m] = ug[m] * rs[m]; rg[m] = (f32x2){dpp_ror1(ug[m][0]), dpp_ror1(ug[m][1])}; lg[m] = (f32x2){dpp_ror15(ug[m][0]), dpp_ror15(ug[m][1])}; }
; #pragma unroll
;                         for (int m = 0; m < 4; ++m) { const f32x2 pg_ = (m > 0 && f0) ? rg[m > 0 ? m - 1 : 0] : rg[m], ng_ = (m < 3 && f15) ? lg[m < 3 ? m + 1 : 3] : lg[m];
;                             const f32x2 cgt = bg + wg0 * pg_ + wg1 * ug[m] + wg2 * ng_;
;                             const f32x2 e = cgt * (-LOG2E);
;                             const f32x2 d = (f32x2){__builtin_amdgcn_exp2f(e[0]), __builtin_amdgcn_exp2f(e[1])} + 1.f;
;                             const f32x2 sg = {__builtin_amdgcn_rcpf(d[0]), __builtin_amdgcn_rcpf(d[1])};
;                             const f32x2 ov = cv[m] * cgt * sg;
;                             outw[m][n][jp] = cvtpk(ov[0], ov[1]); }
	v_pk_mul_f32 v[62:63], v[62:63], v[178:179] op_sel_hi:[1,0]
	v_pk_mul_f32 v[58:59], v[58:59], v[180:181] op_sel_hi:[1,0]
	v_pk_mul_f32 v[54:55], v[54:55], v[182:183] op_sel_hi:[1,0]
	v_pk_mul_f32 v[50:51], v[50:51], v[144:145] op_sel_hi:[1,0]
	v_pk_mul_f32 v[46:47], v[46:47], v[178:179] op_sel_hi:[1,0]
	v_pk_mul_f32 v[42:43], v[42:43], v[180:181] op_sel_hi:[1,0]
	v_pk_mul_f32 v[38:39], v[38:39], v[182:183] op_sel_hi:[1,0]
	v_pk_mul_f32 v[34:35], v[34:35], v[144:145] op_sel_hi:[1,0]
	s_nop 1
	v_mov_b32_dpp v248, v50 row_shr:1 row_mask:0xf bank_mask:0xf bound_ctrl:1
	v_mov_b32_dpp v249, v51 row_shr:1 row_mask:0xf bank_mask:0xf bound_ctrl:1
	v_mov_b32_dpp v250, v62 row_shl:1 row_mask:0xf bank_mask:0xf bound_ctrl:1
	v_mov_b32_dpp v251, v63 row_shl:1 row_mask:0xf bank_mask:0xf bound_ctrl:1
	v_pk_fma_f32 v[224:225], v[206:207], v[248:249], v[212:213]
	v_pk_fma_f32 v[226:227], v[206:207], v[62:63], v[212:213]
	v_pk_fma_f32 v[228:229], v[206:207], v[58:59], v[212:213]
	v_pk_fma_f32 v[230:231], v[206:207], v[54:55], v[212:213]
	v_pk_fma_f32 v[224:225], v[208:209], v[62:63], v[224:225]
	v_pk_fma_f32 v[226:227], v[208:209], v[58:59], v[226:227]
	v_pk_fma_f32 v[228:229], v[208:209], v[54:55], v[228:229]
	v_pk_fma_f32 v[230:231], v[208:209], v[50:51], v[230:231]
	v_pk_fma_f32 v[224:225], v[210:211], v[58:59], v[224:225]
	v_pk_fma_f32 v[226:227], v[210:211], v[54:55], v[226:227]
	v_pk_fma_f32 v[228:229], v[210:211], v[50:51], v[228:229]
	v_pk_fma_f32 v[230:231], v[210:211], v[250:251], v[230:231]
	s_nop 1
	v_mov_b32_dpp v248, v34 row_shr:1 row_mask:0xf bank_mask:0xf bound_ctrl:1
	v_mov_b32_dpp v249, v35 row_shr:1 row_mask:0xf bank_mask:0xf bound_ctrl:1
	v_mov_b32_dpp v250, v46 row_shl:1 row_mask:0xf bank_mask:0xf bound_ctrl:1
	v_mov_b32_dpp v251, v47 row_shl:1 row_mask:0xf bank_mask:0xf bound_ctrl:1
	v_pk_fma_f32 v[232:233], v[214:215], v[248:249], v[220:221]
	v_pk_fma_f32 v[234:235], v[214:215], v[46:47], v[220:221]
	v_pk_fma_f32 v[236:237], v[214:215], v[42:43], v[220:221]
	v_pk_fma_f32 v[238:239], v[214:215], v[38:39], v[220:221]
	v_pk_fma_f32 v[232:233], v[216:217], v[46:47], v[232:233]
	v_pk_fma_f32 v[234:235], v[216:217], v[42:43], v[234:235]
	v_pk_fma_f32 v[236:237], v[216:217], v[38:39], v[236:237]
	v_pk_fma_f32 v[238:239], v[216:217], v[34:35], v[238:239]
	v_pk_fma_f32 v[232:233], v[218:219], v[42:43], v[232:233]
	v_pk_fma_f32 v[234:235], v[218:219], v[38:39], v[234:235]
	v_pk_fma_f32 v[236:237], v[218:219], v[34:35], v[236:237]
	v_pk_fma_f32 v[238:239], v[218:219], v[250:251], v[238:239]
	v_exp_f32_e64 v240, -v232
	v_exp_f32_e64 v241, -v233
	v_exp_f32_e64 v242, -v234
	v_exp_f32_e64 v243, -v235
	v_exp_f32_e64 v244, -v236
	v_exp_f32_e64 v245, -v237
	v_exp_f32_e64 v246, -v238
	v_exp_f32_e64 v247, -v239
	v_pk_mul_f32 v[224:225], v[224:225], v[232:233]
	v_pk_mul_f32 v[226:227], v[226:227], v[234:235]
	v_pk_mul_f32 v[228:229], v[228:229], v[236:237]
	v_pk_mul_f32 v[230:231], v[230:231], v[238:239]
	v_pk_add_f32 v[240:241], v[240:241], 1.0 op_sel_hi:[1,0]
	v_pk_add_f32 v[242:243], v[242:243], 1.0 op_sel_hi:[1,0]
	v_pk_add_f32 v[244:245], v[244:245], 1.0 op_sel_hi:[1,0]
	v_pk_add_f32 v[246:247], v[246:247], 1.0 op_sel_hi:[1,0]
	v_rcp_f32_e32 v240, v240
	v_rcp_f32_e32 v241, v241
	v_rcp_f32_e32 v242, v242
	v_rcp_f32_e32 v243, v243
	v_rcp_f32_e32 v244, v244
	v_rcp_f32_e32 v245, v245
	v_rcp_f32_e32 v246, v246
	v_rcp_f32_e32 v247, v247
	s_nop 0
	v_pk_mul_f32 v[224:225], v[224:225], v[240:241]
	v_pk_mul_f32 v[226:227], v[226:227], v[242:243]
	v_pk_mul_f32 v[228:229], v[228:229], v[244:245]
	v_pk_mul_f32 v[230:231], v[230:231], v[246:247]
	v_cvt_pk_bf16_f32 v129, v224, v225
	v_cvt_pk_bf16_f32 v133, v226, v227
	v_cvt_pk_bf16_f32 v137, v228, v229
	v_cvt_pk_bf16_f32 v141, v230, v231
	global_load_dwordx4 v[206:209], v172, s[100:101] offset:192
	global_load_dwordx4 v[210:213], v172, s[100:101] offset:208
	global_load_dwordx4 v[214:217], v172, s[100:101] offset:224
	global_load_dwordx4 v[218:221], v172, s[100:101] offset:240
	s_waitcnt vmcnt(4)
	v_pk_mul_f32 v[28:29], v[28:29], v[178:179] op_sel_hi:[1,0]
	v_pk_mul_f32 v[24:25], v[24:25], v[180:181] op_sel_hi:[1,0]
	v_pk_mul_f32 v[20:21], v[20:21], v[182:183] op_sel_hi:[1,0]
	v_pk_mul_f32 v[16:17], v[16:17], v[144:145] op_sel_hi:[1,0]
	v_pk_mul_f32 v[12:13], v[12:13], v[178:179] op_sel_hi:[1,0]
	v_pk_mul_f32 v[8:9], v[8:9], v[180:181] op_sel_hi:[1,0]
	v_pk_mul_f32 v[4:5], v[4:5], v[182:183] op_sel_hi:[1,0]
	v_pk_mul_f32 v[0:1], v[0:1], v[144:145] op_sel_hi:[1,0]
	s_nop 1
	v_mov_b32_dpp v248, v16 row_shr:1 row_mask:0xf bank_mask:0xf bound_ctrl:1
	v_mov_b32_dpp v249, v17 row_shr:1 row_mask:0xf bank_mask:0xf bound_ctrl:1
	v_mov_b32_dpp v250, v28 row_shl:1 row_mask:0xf bank_mask:0xf bound_ctrl:1
	v_mov_b32_dpp v251, v29 row_shl:1 row_mask:0xf bank_mask:0xf bound_ctrl:1
	v_pk_fma_f32 v[224:225], v[190:191], v[248:249], v[196:197]
	v_pk_fma_f32 v[226:227], v[190:191], v[28:29], v[196:197]
	v_pk_fma_f32 v[228:229], v[190:191], v[24:25], v[196:197]
	v_pk_fma_f32 v[230:231], v[190:191], v[20:21], v[196:197]
	v_pk_fma_f32 v[224:225], v[192:193], v[28:29], v[224:225]
	v_pk_fma_f32 v[226:227], v[192:193], v[24:25], v[226:227]
	v_pk_fma_f32 v[228:229], v[192:193], v[20:21], v[228:229]
	v_pk_fma_f32 v[230:231], v[192:193], v[16:17], v[230:231]
	v_pk_fma_f32 v[224:225], v[194:195], v[24:25], v[224:225]
	v_pk_fma_f32 v[226:227], v[194:195], v[20:21], v[226:227]
	v_pk_fma_f32 v[228:229], v[194:195], v[16:17], v[228:229]
	v_pk_fma_f32 v[230:231], v[194:195], v[250:251], v[230:231]
	s_nop 1
	v_mov_b32_dpp v248, v0 row_shr:1 row_mask:0xf bank_mask:0xf bound_ctrl:1
	v_mov_b32_dpp v249, v1 row_shr:1 row_mask:0xf bank_mask:0xf bound_ctrl:1
;     __device__ __forceinline__ void operator()(const f32x4 (&acc)[2][2][4][2], const Unit& u, int wr, int wc, int fr, int fq) const {
;     ...
;                         for (int m = 0; m < 4; ++m) { uv[m] = uv[m] * rs[m]; rv[m] = (f32x2){dpp_ror1(uv[m][0]), dpp_ror1(uv[m][1])}; lv[m] = (f32x2){dpp_ror15(uv[m][0]), dpp_ror15(uv[m][1])}; }
; #pragma unroll
;                         for (int m = 0; m < 4; ++m) { const f32x2 pv_ = (m > 0 && f0) ? rv[m > 0 ? m - 1 : 0] : rv[m], nv_ = (m < 3 && f15) ? lv[m < 3 ? m + 1 : 3] : lv[m];
;                             cv[m] = bv + wv0 * pv_ + wv1 * uv[m] + wv2 * nv_; }
;                     }
;                     asm volatile("" : "+v"(cv[0]), "+v"(cv[1]), "+v"(cv[2]), "+v"(cv[3]));
;                     {
;                         f32x2 rg[4], lg[4];
; #pragma unroll
;                         for (int m = 0; m < 4; ++m) { ug[m] = ug[m] * rs[m]; rg[m] = (f32x2){dpp_ror1(ug[m][0]), dpp_ror1(ug[m][1])}; lg[m] = (f32x2){dpp_ror15(ug[m][0]), dpp_ror15(ug[m][1])}; }
; #pragma unroll
;                         for (int m = 0; m < 4; ++m) { const f32x2 pg_ = (m > 0 && f0) ? rg[m > 0 ? m - 1 : 0] : rg[m], ng_ = (m < 3 && f15) ? lg[m < 3 ? m + 1 : 3] : lg[m];
;                             const f32x2 cgt = bg + wg0 * pg_ + wg1 * ug[m] + wg2 * ng_;
;                             const f32x2 e = cgt * (-LOG2E);
;                             const f32x2 d = (f32x2){__builtin_amdgcn_exp2f(e[0]), __builtin_amdgcn_exp2f(e[1])} + 1.f;
;                             const f32x2 sg = {__builtin_amdgcn_rcpf(d[0]), __builtin_amdgcn_rcpf(d[1])};
;                             const f32x2 ov = cv[m] * cgt * sg;
;                             outw[m][n][jp] = cvtpk(ov[0], ov[1]); }
;                     }
;                     asm volatile("" : "+v"(outw[0][n][jp]), "+v"(outw[1][n][jp]), "+v"(outw[2][n][jp]), "+v"(outw[3][n][jp]) :: "memory"); __builtin_amdgcn_sched_barrier(0);
;                 }
; #pragma unroll
;             for (int m = 0; m < 4; ++m) { const int i = 16 * m + fr, t = tbase + i;
;                 if (i >= 1 && i <= 62 && t < slen) { u32x4 w; w.x = outw[m][0][0]; w.y = outw[m][0][1]; w.z = outw[m][1][0]; w.w = outw[m][1][1];
;                     *(u32x4*)(Gout + (size_t)(seqbase + t) * DFF + 128 * u.pn + 32 * wc + 8 * fq) = w; } }
	v_mov_b32_dpp v250, v12 row_shl:1 row_mask:0xf bank_mask:0xf bound_ctrl:1
	v_mov_b32_dpp v251, v13 row_shl:1 row_mask:0xf bank_mask:0xf bound_ctrl:1
	v_pk_fma_f32 v[232:233], v[198:199], v[248:249], v[204:205]
	v_pk_fma_f32 v[234:235], v[198:199], v[12:13], v[204:205]
	v_pk_fma_f32 v[236:237], v[198:199], v[8:9], v[204:205]
	v_pk_fma_f32 v[238:239], v[198:199], v[4:5], v[204:205]
	v_pk_fma_f32 v[232:233], v[200:201], v[12:13], v[232:233]
	v_pk_fma_f32 v[234:235], v[200:201], v[8:9], v[234:235]
	v_pk_fma_f32 v[236:237], v[200:201], v[4:5], v[236:237]
	v_pk_fma_f32 v[238:239], v[200:201], v[0:1], v[238:239]
	v_pk_fma_f32 v[232:233], v[202:203], v[8:9], v[232:233]
	v_pk_fma_f32 v[234:235], v[202:203], v[4:5], v[234:235]
	v_pk_fma_f32 v[236:237], v[202:203], v[0:1], v[236:237]
	v_pk_fma_f32 v[238:239], v[202:203], v[250:251], v[238:239]
	v_exp_f32_e64 v240, -v232
	v_exp_f32_e64 v241, -v233
	v_exp_f32_e64 v242, -v234
	v_exp_f32_e64 v243, -v235
	v_exp_f32_e64 v244, -v236
	v_exp_f32_e64 v245, -v237
	v_exp_f32_e64 v246, -v238
	v_exp_f32_e64 v247, -v239
	v_pk_mul_f32 v[224:225], v[224:225], v[232:233]
	v_pk_mul_f32 v[226:227], v[226:227], v[234:235]
	v_pk_mul_f32 v[228:229], v[228:229], v[236:237]
	v_pk_mul_f32 v[230:231], v[230:231], v[238:239]
	v_pk_add_f32 v[240:241], v[240:241], 1.0 op_sel_hi:[1,0]
	v_pk_add_f32 v[242:243], v[242:243], 1.0 op_sel_hi:[1,0]
	v_pk_add_f32 v[244:245], v[244:245], 1.0 op_sel_hi:[1,0]
	v_pk_add_f32 v[246:247], v[246:247], 1.0 op_sel_hi:[1,0]
	v_rcp_f32_e32 v240, v240
	v_rcp_f32_e32 v241, v241
	v_rcp_f32_e32 v242, v242
	v_rcp_f32_e32 v243, v243
	v_rcp_f32_e32 v244, v244
	v_rcp_f32_e32 v245, v245
	v_rcp_f32_e32 v246, v246
	v_rcp_f32_e32 v247, v247
	s_nop 0
	v_pk_mul_f32 v[224:225], v[224:225], v[240:241]
	v_pk_mul_f32 v[226:227], v[226:227], v[242:243]
	v_pk_mul_f32 v[228:229], v[228:229], v[244:245]
	v_pk_mul_f32 v[230:231], v[230:231], v[246:247]
	v_cvt_pk_bf16_f32 v130, v224, v225
	v_cvt_pk_bf16_f32 v134, v226, v227
	v_cvt_pk_bf16_f32 v138, v228, v229
	v_cvt_pk_bf16_f32 v142, v230, v231
	s_waitcnt vmcnt(0)
	v_pk_mul_f32 v[30:31], v[30:31], v[178:179] op_sel_hi:[1,0]
	v_pk_mul_f32 v[26:27], v[26:27], v[180:181] op_sel_hi:[1,0]
	v_pk_mul_f32 v[22:23], v[22:23], v[182:183] op_sel_hi:[1,0]
	v_pk_mul_f32 v[18:19], v[18:19], v[144:145] op_sel_hi:[1,0]
	v_pk_mul_f32 v[14:15], v[14:15], v[178:179] op_sel_hi:[1,0]
	v_pk_mul_f32 v[10:11], v[10:11], v[180:181] op_sel_hi:[1,0]
	v_pk_mul_f32 v[6:7], v[6:7], v[182:183] op_sel_hi:[1,0]
	v_pk_mul_f32 v[2:3], v[2:3], v[144:145] op_sel_hi:[1,0]
	s_nop 1
	v_mov_b32_dpp v248, v18 row_shr:1 row_mask:0xf bank_mask:0xf bound_ctrl:1
	v_mov_b32_dpp v249, v19 row_shr:1 row_mask:0xf bank_mask:0xf bound_ctrl:1
	v_mov_b32_dpp v250, v30 row_shl:1 row_mask:0xf bank_mask:0xf bound_ctrl:1
	v_mov_b32_dpp v251, v31 row_shl:1 row_mask:0xf bank_mask:0xf bound_ctrl:1
	v_pk_fma_f32 v[224:225], v[206:207], v[248:249], v[212:213]
	v_pk_fma_f32 v[226:227], v[206:207], v[30:31], v[212:213]
	v_pk_fma_f32 v[228:229], v[206:207], v[26:27], v[212:213]
	v_pk_fma_f32 v[230:231], v[206:207], v[22:23], v[212:213]
	v_pk_fma_f32 v[224:225], v[208:209], v[30:31], v[224:225]
	v_pk_fma_f32 v[226:227], v[208:209], v[26:27], v[226:227]
	v_pk_fma_f32 v[228:229], v[208:209], v[22:23], v[228:229]
	v_pk_fma_f32 v[230:231], v[208:209], v[18:19], v[230:231]
	v_pk_fma_f32 v[224:225], v[210:211], v[26:27], v[224:225]
	v_pk_fma_f32 v[226:227], v[210:211], v[22:23], v[226:227]
	v_pk_fma_f32 v[228:229], v[210:211], v[18:19], v[228:229]
	v_pk_fma_f32 v[230:231], v[210:211], v[250:251], v[230:231]
	s_nop 1
	v_mov_b32_dpp v248, v2 row_shr:1 row_mask:0xf bank_mask:0xf bound_ctrl:1
	v_mov_b32_dpp v249, v3 row_shr:1 row_mask:0xf bank_mask:0xf bound_ctrl:1
	v_mov_b32_dpp v250, v14 row_shl:1 row_mask:0xf bank_mask:0xf bound_ctrl:1
	v_mov_b32_dpp v251, v15 row_shl:1 row_mask:0xf bank_mask:0xf bound_ctrl:1
	v_pk_fma_f32 v[232:233], v[214:215], v[248:249], v[220:221]
	v_pk_fma_f32 v[234:235], v[214:215], v[14:15], v[220:221]
	v_pk_fma_f32 v[236:237], v[214:215], v[10:11], v[220:221]
	v_pk_fma_f32 v[238:239], v[214:215], v[6:7], v[220:221]
	v_pk_fma_f32 v[232:233], v[216:217], v[14:15], v[232:233]
	v_pk_fma_f32 v[234:235], v[216:217], v[10:11], v[234:235]
	v_pk_fma_f32 v[236:237], v[216:217], v[6:7], v[236:237]
	v_pk_fma_f32 v[238:239], v[216:217], v[2:3], v[238:239]
	v_pk_fma_f32 v[232:233], v[218:219], v[10:11], v[232:233]
	v_pk_fma_f32 v[234:235], v[218:219], v[6:7], v[234:235]
	v_pk_fma_f32 v[236:237], v[218:219], v[2:3], v[236:237]
	v_pk_fma_f32 v[238:239], v[218:219], v[250:251], v[238:239]
	v_exp_f32_e64 v240, -v232
	v_exp_f32_e64 v241, -v233
	v_exp_f32_e64 v242, -v234
	v_exp_f32_e64 v243, -v235
	v_exp_f32_e64 v244, -v236
	v_exp_f32_e64 v245, -v237
	v_exp_f32_e64 v246, -v238
	v_exp_f32_e64 v247, -v239
	v_pk_mul_f32 v[224:225], v[224:225], v[232:233]
	v_pk_mul_f32 v[226:227], v[226:227], v[234:235]
	v_pk_mul_f32 v[228:229], v[228:229], v[236:237]
	v_pk_mul_f32 v[230:231], v[230:231], v[238:239]
	v_pk_add_f32 v[240:241], v[240:241], 1.0 op_sel_hi:[1,0]
	v_pk_add_f32 v[242:243], v[242:243], 1.0 op_sel_hi:[1,0]
	v_pk_add_f32 v[244:245], v[244:245], 1.0 op_sel_hi:[1,0]
	v_pk_add_f32 v[246:247], v[246:247], 1.0 op_sel_hi:[1,0]
	v_rcp_f32_e32 v240, v240
	v_rcp_f32_e32 v241, v241
	v_rcp_f32_e32 v242, v242
	v_rcp_f32_e32 v243, v243
	v_rcp_f32_e32 v244, v244
	v_rcp_f32_e32 v245, v245
	v_rcp_f32_e32 v246, v246
	v_rcp_f32_e32 v247, v247
	s_nop 0
	v_pk_mul_f32 v[224:225], v[224:225], v[240:241]
	v_pk_mul_f32 v[226:227], v[226:227], v[242:243]
	v_pk_mul_f32 v[228:229], v[228:229], v[244:245]
	v_pk_mul_f32 v[230:231], v[230:231], v[246:247]
	v_cvt_pk_bf16_f32 v131, v224, v225
	v_cvt_pk_bf16_f32 v135, v226, v227
	v_cvt_pk_bf16_f32 v139, v228, v229
	v_cvt_pk_bf16_f32 v143, v230, v231
	v_add_u32_e32 v176, 0, v174
	v_cmp_gt_u32_e32 vcc, s91, v176
	v_cmp_ne_u32_e64 s[52:53], 0, v170
	s_and_b64 vcc, vcc, s[52:53]
	v_add_u32_e32 v176, s88, v176
	v_mad_u32_u24 v248, v176, s54, v171
	s_and_saveexec_b64 s[64:65], vcc
	global_store_dwordx4 v248, v[128:131], s[86:87]
	s_mov_b64 exec, s[64:65]
	v_add_u32_e32 v176, 1, v174
	v_cmp_gt_u32_e32 vcc, s91, v176
	v_add_u32_e32 v176, s88, v176
	v_mad_u32_u24 v249, v176, s54, v171
	s_and_saveexec_b64 s[64:65], vcc
	global_store_dwordx4 v249, v[132:135], s[86:87]
	s_mov_b64 exec, s[64:65]
	v_add_u32_e32 v176, 2, v174
	v_cmp_gt_u32_e32 vcc, s91, v176
	v_add_u32_e32 v176, s88, v176
	v_mad_u32_u24 v250, v176, s54, v171
	s_and_saveexec_b64 s[64:65], vcc
	global_store_dwordx4 v250, v[136:139], s[86:87]
	s_mov_b64 exec, s[64:65]
	v_add_u32_e32 v176, 3, v174
	v_cmp_gt_u32_e32 vcc, s91, v176
	v_cmp_ne_u32_e64 s[52:53], 60, v170
	s_and_b64 vcc, vcc, s[52:53]
	v_add_u32_e32 v176, s88, v176
	v_mad_u32_u24 v251, v176, s54, v171
	s_and_saveexec_b64 s[64:65], vcc
	global_store_dwordx4 v251, v[140:143], s[86:87]
	s_mov_b64 exec, s[64:65]
	s_mov_b64 s[2:3], exec
